# P1 plain epilogue: H stores in saddr form (s[14:15] + 32-bit VGPR offset), 44 64-bit address VALU ops removed
# speedup vs baseline: 1.0050x; 1.0050x over previous
.LBB0_108:
	s_mov_b32 s98, 0
	v_lshl_add_u32 v146, s46, 8, v152
	s_cmpk_lg_i32 s18, 0x4c
	s_mov_b64 s[0:1], -1
	v_readlane_b32 s61, v254, 34
	s_cbranch_scc0 .LBB0_115
	s_cmp_lt_i32 s18, 60
	s_cbranch_scc0 .LBB0_111
	s_lshl_b32 s78, s18, 22
	v_lshl_add_u32 v174, v146, 9, v0
	v_add_u32_e32 v174, s78, v174
	v_add_u32_e32 v175, 0x2000, v174
	v_add_u32_e32 v176, 0x4000, v174
	v_add_u32_e32 v177, 0x6000, v174
	v_add_u32_e32 v178, 0x10000, v174
	v_add_u32_e32 v179, 0x12000, v174
	v_add_u32_e32 v180, 0x14000, v174
	v_add_u32_e32 v181, 0x16000, v174
	s_mov_b32 s98, 16
	s_and_b32 s0, s18, -4
	s_cmp_eq_u32 s0, 36
	v_pk_mul_f32 v[156:157], v[72:73], s[26:27] op_sel_hi:[1,0]
	v_pk_mul_f32 v[158:159], v[70:71], s[26:27] op_sel_hi:[1,0]
	v_pk_mul_f32 v[160:161], v[68:69], s[26:27] op_sel_hi:[1,0]
	v_pk_mul_f32 v[162:163], v[66:67], s[26:27] op_sel_hi:[1,0]
	s_cselect_b64 vcc, -1, 0
	v_cndmask_b32_e32 v147, v73, v157, vcc
	v_cndmask_b32_e32 v157, v72, v156, vcc
	v_cndmask_b32_e32 v156, v71, v159, vcc
	v_cndmask_b32_e32 v158, v70, v158, vcc
	v_cndmask_b32_e32 v159, v69, v161, vcc
	v_cndmask_b32_e32 v160, v68, v160, vcc
	v_cndmask_b32_e32 v161, v67, v163, vcc
	v_cndmask_b32_e32 v162, v66, v162, vcc
	v_cvt_pk_bf16_f32 v156, v158, v156
	v_cvt_pk_bf16_f32 v157, v157, v147
	v_cvt_pk_bf16_f32 v158, v162, v161
	v_cvt_pk_bf16_f32 v159, v160, v159
	global_store_dwordx4 v174, v[156:159], s[14:15]
	s_nop 1
	v_pk_mul_f32 v[160:161], v[124:125], s[26:27] op_sel_hi:[1,0]
	v_pk_mul_f32 v[162:163], v[122:123], s[26:27] op_sel_hi:[1,0]
	v_pk_mul_f32 v[156:157], v[128:129], s[26:27] op_sel_hi:[1,0]
	v_pk_mul_f32 v[158:159], v[126:127], s[26:27] op_sel_hi:[1,0]
	v_cndmask_b32_e32 v147, v129, v157, vcc
	v_cndmask_b32_e32 v157, v128, v156, vcc
	v_cndmask_b32_e32 v156, v127, v159, vcc
	v_cndmask_b32_e32 v158, v126, v158, vcc
	v_cndmask_b32_e32 v159, v125, v161, vcc
	v_cndmask_b32_e32 v160, v124, v160, vcc
	v_cndmask_b32_e32 v161, v123, v163, vcc
	v_cndmask_b32_e32 v162, v122, v162, vcc
	v_cvt_pk_bf16_f32 v156, v158, v156
	v_cvt_pk_bf16_f32 v157, v157, v147
	v_cvt_pk_bf16_f32 v158, v162, v161
	v_cvt_pk_bf16_f32 v159, v160, v159
	global_store_dwordx4 v174, v[156:159], s[14:15] offset:256
	s_nop 1
	v_pk_mul_f32 v[162:163], v[60:61], s[26:27] op_sel_hi:[1,0]
	v_pk_mul_f32 v[164:165], v[58:59], s[26:27] op_sel_hi:[1,0]
	v_pk_mul_f32 v[156:157], v[64:65], s[26:27] op_sel_hi:[1,0]
	v_pk_mul_f32 v[158:159], v[62:63], s[26:27] op_sel_hi:[1,0]
	v_cndmask_b32_e32 v147, v65, v157, vcc
	v_cndmask_b32_e32 v157, v64, v156, vcc
	v_cndmask_b32_e32 v156, v63, v159, vcc
	v_cndmask_b32_e32 v158, v62, v158, vcc
	v_cndmask_b32_e32 v159, v61, v163, vcc
	v_cndmask_b32_e32 v162, v60, v162, vcc
	v_cndmask_b32_e32 v163, v59, v165, vcc
	v_cndmask_b32_e32 v164, v58, v164, vcc
	v_cvt_pk_bf16_f32 v156, v158, v156
	v_cvt_pk_bf16_f32 v157, v157, v147
	v_cvt_pk_bf16_f32 v158, v164, v163
	v_cvt_pk_bf16_f32 v159, v162, v159
	global_store_dwordx4 v175, v[156:159], s[14:15]
	s_nop 1
	v_pk_mul_f32 v[162:163], v[116:117], s[26:27] op_sel_hi:[1,0]
	v_pk_mul_f32 v[164:165], v[114:115], s[26:27] op_sel_hi:[1,0]
	v_pk_mul_f32 v[156:157], v[120:121], s[26:27] op_sel_hi:[1,0]
	v_pk_mul_f32 v[158:159], v[118:119], s[26:27] op_sel_hi:[1,0]
	v_cndmask_b32_e32 v147, v121, v157, vcc
	v_cndmask_b32_e32 v157, v120, v156, vcc
	v_cndmask_b32_e32 v156, v119, v159, vcc
	v_cndmask_b32_e32 v158, v118, v158, vcc
	v_cndmask_b32_e32 v159, v117, v163, vcc
	v_cndmask_b32_e32 v162, v116, v162, vcc
	v_cndmask_b32_e32 v163, v115, v165, vcc
	v_cndmask_b32_e32 v164, v114, v164, vcc
	v_cvt_pk_bf16_f32 v156, v158, v156
	v_cvt_pk_bf16_f32 v157, v157, v147
	v_cvt_pk_bf16_f32 v158, v164, v163
	v_cvt_pk_bf16_f32 v159, v162, v159
	global_store_dwordx4 v175, v[156:159], s[14:15] offset:256
	s_nop 1
	v_pk_mul_f32 v[162:163], v[48:49], s[26:27] op_sel_hi:[1,0]
	v_pk_mul_f32 v[164:165], v[46:47], s[26:27] op_sel_hi:[1,0]
	v_pk_mul_f32 v[156:157], v[52:53], s[26:27] op_sel_hi:[1,0]
	v_pk_mul_f32 v[158:159], v[50:51], s[26:27] op_sel_hi:[1,0]
	v_cndmask_b32_e32 v147, v53, v157, vcc
	v_cndmask_b32_e32 v157, v52, v156, vcc
	v_cndmask_b32_e32 v156, v51, v159, vcc
	v_cndmask_b32_e32 v158, v50, v158, vcc
	v_cndmask_b32_e32 v159, v49, v163, vcc
	v_cndmask_b32_e32 v162, v48, v162, vcc
	v_cndmask_b32_e32 v163, v47, v165, vcc
	v_cndmask_b32_e32 v164, v46, v164, vcc
	v_cvt_pk_bf16_f32 v156, v158, v156
	v_cvt_pk_bf16_f32 v157, v157, v147
	v_cvt_pk_bf16_f32 v158, v164, v163
	v_cvt_pk_bf16_f32 v159, v162, v159
	global_store_dwordx4 v176, v[156:159], s[14:15]
	s_nop 1
	v_pk_mul_f32 v[162:163], v[108:109], s[26:27] op_sel_hi:[1,0]
	v_pk_mul_f32 v[164:165], v[106:107], s[26:27] op_sel_hi:[1,0]
	v_pk_mul_f32 v[156:157], v[112:113], s[26:27] op_sel_hi:[1,0]
	v_pk_mul_f32 v[158:159], v[110:111], s[26:27] op_sel_hi:[1,0]
	v_cndmask_b32_e32 v147, v113, v157, vcc
	v_cndmask_b32_e32 v157, v112, v156, vcc
	v_cndmask_b32_e32 v156, v111, v159, vcc
	v_cndmask_b32_e32 v158, v110, v158, vcc
	v_cndmask_b32_e32 v159, v109, v163, vcc
	v_cndmask_b32_e32 v162, v108, v162, vcc
	v_cndmask_b32_e32 v163, v107, v165, vcc
	v_cndmask_b32_e32 v164, v106, v164, vcc
	v_cvt_pk_bf16_f32 v156, v158, v156
	v_cvt_pk_bf16_f32 v157, v157, v147
	v_cvt_pk_bf16_f32 v158, v164, v163
	v_cvt_pk_bf16_f32 v159, v162, v159
	global_store_dwordx4 v176, v[156:159], s[14:15] offset:256
	s_nop 1
	v_pk_mul_f32 v[160:161], v[40:41], s[26:27] op_sel_hi:[1,0]
	v_pk_mul_f32 v[162:163], v[38:39], s[26:27] op_sel_hi:[1,0]
	v_pk_mul_f32 v[156:157], v[44:45], s[26:27] op_sel_hi:[1,0]
	v_pk_mul_f32 v[158:159], v[42:43], s[26:27] op_sel_hi:[1,0]
	v_cndmask_b32_e32 v147, v45, v157, vcc
	v_cndmask_b32_e32 v157, v44, v156, vcc
	v_cndmask_b32_e32 v156, v43, v159, vcc
	v_cndmask_b32_e32 v158, v42, v158, vcc
	v_cndmask_b32_e32 v159, v41, v161, vcc
	v_cndmask_b32_e32 v160, v40, v160, vcc
	v_cndmask_b32_e32 v161, v39, v163, vcc
	v_cndmask_b32_e32 v162, v38, v162, vcc
	v_cvt_pk_bf16_f32 v156, v158, v156
	v_cvt_pk_bf16_f32 v157, v157, v147
	v_cvt_pk_bf16_f32 v158, v162, v161
	v_cvt_pk_bf16_f32 v159, v160, v159
	global_store_dwordx4 v177, v[156:159], s[14:15]
	s_nop 1
	v_pk_mul_f32 v[160:161], v[100:101], s[26:27] op_sel_hi:[1,0]
	v_pk_mul_f32 v[162:163], v[98:99], s[26:27] op_sel_hi:[1,0]
	v_pk_mul_f32 v[156:157], v[104:105], s[26:27] op_sel_hi:[1,0]
	v_pk_mul_f32 v[158:159], v[102:103], s[26:27] op_sel_hi:[1,0]
	v_cndmask_b32_e32 v147, v105, v157, vcc
	v_cndmask_b32_e32 v157, v104, v156, vcc
	v_cndmask_b32_e32 v156, v103, v159, vcc
	v_cndmask_b32_e32 v158, v102, v158, vcc
	v_cndmask_b32_e32 v159, v101, v161, vcc
	v_cndmask_b32_e32 v160, v100, v160, vcc
	v_cndmask_b32_e32 v161, v99, v163, vcc
	v_cndmask_b32_e32 v162, v98, v162, vcc
	v_cvt_pk_bf16_f32 v156, v158, v156
	v_cvt_pk_bf16_f32 v157, v157, v147
	v_cvt_pk_bf16_f32 v158, v162, v161
	v_cvt_pk_bf16_f32 v159, v160, v159
	global_store_dwordx4 v177, v[156:159], s[14:15] offset:256
	s_nop 1
	v_pk_mul_f32 v[160:161], v[28:29], s[26:27] op_sel_hi:[1,0]
	v_pk_mul_f32 v[156:157], v[32:33], s[26:27] op_sel_hi:[1,0]
	v_pk_mul_f32 v[158:159], v[30:31], s[26:27] op_sel_hi:[1,0]
	v_pk_mul_f32 v[162:163], v[26:27], s[26:27] op_sel_hi:[1,0]
	v_cndmask_b32_e32 v147, v33, v157, vcc
	v_cndmask_b32_e32 v157, v32, v156, vcc
	v_cndmask_b32_e32 v156, v31, v159, vcc
	v_cndmask_b32_e32 v159, v29, v161, vcc
	v_cndmask_b32_e32 v160, v28, v160, vcc
	v_cndmask_b32_e32 v158, v30, v158, vcc
	v_cndmask_b32_e32 v161, v27, v163, vcc
	v_cndmask_b32_e32 v162, v26, v162, vcc
	v_cvt_pk_bf16_f32 v159, v160, v159
	v_cvt_pk_bf16_f32 v156, v158, v156
	v_cvt_pk_bf16_f32 v157, v157, v147
	v_cvt_pk_bf16_f32 v158, v162, v161
	global_store_dwordx4 v178, v[156:159], s[14:15]
	s_nop 1
	v_pk_mul_f32 v[160:161], v[92:93], s[26:27] op_sel_hi:[1,0]
	v_pk_mul_f32 v[162:163], v[90:91], s[26:27] op_sel_hi:[1,0]
	v_pk_mul_f32 v[156:157], v[96:97], s[26:27] op_sel_hi:[1,0]
	v_pk_mul_f32 v[158:159], v[94:95], s[26:27] op_sel_hi:[1,0]
	v_cndmask_b32_e32 v147, v97, v157, vcc
	v_cndmask_b32_e32 v157, v96, v156, vcc
	v_cndmask_b32_e32 v156, v95, v159, vcc
	v_cndmask_b32_e32 v158, v94, v158, vcc
	v_cndmask_b32_e32 v159, v93, v161, vcc
	v_cndmask_b32_e32 v160, v92, v160, vcc
	v_cndmask_b32_e32 v161, v91, v163, vcc
	v_cndmask_b32_e32 v162, v90, v162, vcc
	v_cvt_pk_bf16_f32 v156, v158, v156
	v_cvt_pk_bf16_f32 v157, v157, v147
	v_cvt_pk_bf16_f32 v158, v162, v161
	v_cvt_pk_bf16_f32 v159, v160, v159
	global_store_dwordx4 v178, v[156:159], s[14:15] offset:256
	s_nop 1
	v_pk_mul_f32 v[160:161], v[20:21], s[26:27] op_sel_hi:[1,0]
	v_pk_mul_f32 v[156:157], v[24:25], s[26:27] op_sel_hi:[1,0]
	v_pk_mul_f32 v[158:159], v[22:23], s[26:27] op_sel_hi:[1,0]
	v_pk_mul_f32 v[162:163], v[18:19], s[26:27] op_sel_hi:[1,0]
	v_cndmask_b32_e32 v147, v25, v157, vcc
	v_cndmask_b32_e32 v157, v24, v156, vcc
	v_cndmask_b32_e32 v156, v23, v159, vcc
	v_cndmask_b32_e32 v159, v21, v161, vcc
	v_cndmask_b32_e32 v160, v20, v160, vcc
	v_cndmask_b32_e32 v158, v22, v158, vcc
	v_cndmask_b32_e32 v161, v19, v163, vcc
	v_cndmask_b32_e32 v162, v18, v162, vcc
	v_cvt_pk_bf16_f32 v159, v160, v159
	v_cvt_pk_bf16_f32 v156, v158, v156
	v_cvt_pk_bf16_f32 v157, v157, v147
	v_cvt_pk_bf16_f32 v158, v162, v161
	global_store_dwordx4 v179, v[156:159], s[14:15]
	s_nop 1
	v_pk_mul_f32 v[160:161], v[84:85], s[26:27] op_sel_hi:[1,0]
	v_pk_mul_f32 v[162:163], v[82:83], s[26:27] op_sel_hi:[1,0]
	v_pk_mul_f32 v[156:157], v[88:89], s[26:27] op_sel_hi:[1,0]
	v_pk_mul_f32 v[158:159], v[86:87], s[26:27] op_sel_hi:[1,0]
	v_cndmask_b32_e32 v147, v89, v157, vcc
	v_cndmask_b32_e32 v157, v88, v156, vcc
	v_cndmask_b32_e32 v156, v87, v159, vcc
	v_cndmask_b32_e32 v158, v86, v158, vcc
	v_cndmask_b32_e32 v159, v85, v161, vcc
	v_cndmask_b32_e32 v160, v84, v160, vcc
	v_cndmask_b32_e32 v161, v83, v163, vcc
	v_cndmask_b32_e32 v162, v82, v162, vcc
	v_cvt_pk_bf16_f32 v156, v158, v156
	v_cvt_pk_bf16_f32 v157, v157, v147
	v_cvt_pk_bf16_f32 v158, v162, v161
	v_cvt_pk_bf16_f32 v159, v160, v159
	global_store_dwordx4 v179, v[156:159], s[14:15] offset:256
	s_nop 1
	v_pk_mul_f32 v[160:161], v[12:13], s[26:27] op_sel_hi:[1,0]
	v_pk_mul_f32 v[156:157], v[16:17], s[26:27] op_sel_hi:[1,0]
	v_pk_mul_f32 v[158:159], v[14:15], s[26:27] op_sel_hi:[1,0]
	v_pk_mul_f32 v[162:163], v[10:11], s[26:27] op_sel_hi:[1,0]
	v_cndmask_b32_e32 v147, v17, v157, vcc
	v_cndmask_b32_e32 v157, v16, v156, vcc
	v_cndmask_b32_e32 v156, v15, v159, vcc
	v_cndmask_b32_e32 v159, v13, v161, vcc
	v_cndmask_b32_e32 v160, v12, v160, vcc
	v_cndmask_b32_e32 v158, v14, v158, vcc
	v_cndmask_b32_e32 v161, v11, v163, vcc
	v_cndmask_b32_e32 v162, v10, v162, vcc
	v_cvt_pk_bf16_f32 v159, v160, v159
	v_cvt_pk_bf16_f32 v156, v158, v156
	v_cvt_pk_bf16_f32 v157, v157, v147
	v_cvt_pk_bf16_f32 v158, v162, v161
	global_store_dwordx4 v180, v[156:159], s[14:15]
	s_nop 1
	v_pk_mul_f32 v[160:161], v[76:77], s[26:27] op_sel_hi:[1,0]
	v_pk_mul_f32 v[162:163], v[74:75], s[26:27] op_sel_hi:[1,0]
	v_pk_mul_f32 v[156:157], v[80:81], s[26:27] op_sel_hi:[1,0]
	v_pk_mul_f32 v[158:159], v[78:79], s[26:27] op_sel_hi:[1,0]
	v_cndmask_b32_e32 v147, v81, v157, vcc
	v_cndmask_b32_e32 v157, v80, v156, vcc
	v_cndmask_b32_e32 v156, v79, v159, vcc
	v_cndmask_b32_e32 v158, v78, v158, vcc
	v_cndmask_b32_e32 v159, v77, v161, vcc
	v_cndmask_b32_e32 v160, v76, v160, vcc
	v_cndmask_b32_e32 v161, v75, v163, vcc
	v_cndmask_b32_e32 v162, v74, v162, vcc
	v_cvt_pk_bf16_f32 v156, v158, v156
	v_cvt_pk_bf16_f32 v157, v157, v147
	v_cvt_pk_bf16_f32 v158, v162, v161
	v_cvt_pk_bf16_f32 v159, v160, v159
	global_store_dwordx4 v180, v[156:159], s[14:15] offset:256
	s_nop 1
	v_pk_mul_f32 v[150:151], v[8:9], s[26:27] op_sel_hi:[1,0]
	v_pk_mul_f32 v[156:157], v[6:7], s[26:27] op_sel_hi:[1,0]
	v_pk_mul_f32 v[158:159], v[4:5], s[26:27] op_sel_hi:[1,0]
	v_pk_mul_f32 v[162:163], v[2:3], s[26:27] op_sel_hi:[1,0]
	v_cndmask_b32_e32 v147, v9, v151, vcc
	v_cndmask_b32_e32 v150, v8, v150, vcc
	v_cndmask_b32_e32 v151, v7, v157, vcc
	v_cndmask_b32_e32 v156, v6, v156, vcc
	v_cndmask_b32_e32 v159, v5, v159, vcc
	v_cndmask_b32_e32 v164, v4, v158, vcc
	v_cndmask_b32_e32 v158, v3, v163, vcc
	v_cndmask_b32_e32 v162, v2, v162, vcc
	v_cvt_pk_bf16_f32 v156, v156, v151
	v_cvt_pk_bf16_f32 v157, v150, v147
	v_cvt_pk_bf16_f32 v158, v162, v158
	v_cvt_pk_bf16_f32 v159, v164, v159
	global_store_dwordx4 v181, v[156:159], s[14:15]
	s_nop 1
	v_pk_mul_f32 v[148:149], v[56:57], s[26:27] op_sel_hi:[1,0]
	v_pk_mul_f32 v[150:151], v[54:55], s[26:27] op_sel_hi:[1,0]
	v_pk_mul_f32 v[156:157], v[36:37], s[26:27] op_sel_hi:[1,0]
	v_pk_mul_f32 v[158:159], v[34:35], s[26:27] op_sel_hi:[1,0]
	v_cndmask_b32_e32 v147, v57, v149, vcc
	v_cndmask_b32_e32 v149, v56, v148, vcc
	v_cndmask_b32_e32 v148, v55, v151, vcc
	v_cndmask_b32_e32 v150, v54, v150, vcc
	v_cndmask_b32_e32 v151, v37, v157, vcc
	v_cndmask_b32_e32 v156, v36, v156, vcc
	v_cndmask_b32_e32 v157, v35, v159, vcc
	v_cndmask_b32_e32 v158, v34, v158, vcc
	v_cvt_pk_bf16_f32 v148, v150, v148
	v_cvt_pk_bf16_f32 v149, v149, v147
	v_cvt_pk_bf16_f32 v150, v158, v157
	v_cvt_pk_bf16_f32 v151, v156, v151
	global_store_dwordx4 v181, v[148:151], s[14:15] offset:256
	s_nop 1
	s_mov_b64 s[0:1], 0
